# code placement: load segments start 8-byte aligned, MFMA runs kept at 4 mod 8, loop heads 64-byte aligned
# speedup vs baseline: 1.0120x; 1.0120x over previous
; #define LAS __attribute__((address_space(3)))
; #define BAR() { __builtin_amdgcn_sched_barrier(0); __builtin_amdgcn_s_barrier(); asm volatile("" ::: "memory"); __builtin_amdgcn_sched_barrier(0); }
; DI void gemm_stream2(const bf16_t* __restrict__ A, int lda, const bf16_t* __restrict__ Bt, int ldb, int K, int m0, int n0, ...
;     ...
; #pragma unroll
;         for (int ks = 0; ks < 2; ++ks) {
;             const unsigned fo = ks ? fo1 : fo0;
;             bf16x8 af[4], bfr[4];
; #pragma unroll
;             for (int i = 0; i < 4; ++i) { af[i] = *(const LAS bf16x8*)(base + aoff + i * 2048 + fo); bfr[i] = *(const LAS bf16x8*)(base + boff + i * 2048 + fo); }
;             if (ks == 1 && more) { if (pf) asm volatile("s_waitcnt vmcnt(3)" ::: "memory"); else asm volatile("s_waitcnt vmcnt(0)" ::: "memory"); }
;             if (pf) { PIECE(s2, ks * 3 + 0); PIECE(s2, ks * 3 + 1); PIECE(s2, ks * 3 + 2); }
;             asm volatile("s_waitcnt lgkmcnt(0)" ::: "memory");
;             BAR();
;             __builtin_amdgcn_s_setprio(1);
; #pragma unroll
;             for (int mi = 0; mi < 4; ++mi)
; #pragma unroll
;                 for (int ni = 0; ni < 4; ++ni) acc[mi][ni] = __builtin_amdgcn_mfma_f32_16x16x32_bf16(bfr[ni], af[mi], acc[mi][ni], 0, 0, 0);
;             __builtin_amdgcn_s_setprio(0);
;             BAR();
;         }
.Lgu_kloop:
	ds_read_b128 v[0:3], v188 offset:16
	ds_read_b128 v[4:7], v189 offset:16
	ds_read_b128 v[8:11], v188 offset:2064
	ds_read_b128 v[12:15], v189 offset:2064
	ds_read_b128 v[196:199], v188 offset:16400
	ds_read_b128 v[200:203], v189 offset:16400
	ds_read_b128 v[204:207], v188 offset:18448
	ds_read_b128 v[208:211], v189 offset:18448
	ds_read_b128 v[152:155], v186 offset:16
	ds_read_b128 v[156:159], v187 offset:16
	ds_read_b128 v[160:163], v186 offset:2064
	ds_read_b128 v[164:167], v187 offset:2064
	ds_read_b128 v[168:171], v186 offset:4112
	ds_read_b128 v[172:175], v187 offset:4112
	ds_read_b128 v[176:179], v186 offset:6160
	ds_read_b128 v[180:183], v187 offset:6160
	s_add_i32 m0, s39, 0xc000
	s_nop 0
	global_load_lds_dwordx4 v184, s[68:69]
	s_add_i32 m0, s39, 0xc400
	s_nop 0
	global_load_lds_dwordx4 v185, s[68:69]
	s_add_u32 s68, s68, 0x80
	s_addc_u32 s69, s69, 0
	s_waitcnt lgkmcnt(0)
	s_waitcnt vmcnt(8)
	s_barrier
	s_setprio 1
	v_mfma_f32_16x16x32_bf16 v[24:27], v[0:3], v[152:155], v[24:27]
	v_mfma_f32_16x16x32_bf16 v[28:31], v[8:11], v[152:155], v[28:31]
	v_mfma_f32_16x16x32_bf16 v[32:35], v[0:3], v[160:163], v[32:35]
	v_mfma_f32_16x16x32_bf16 v[36:39], v[8:11], v[160:163], v[36:39]
	v_mfma_f32_16x16x32_bf16 v[40:43], v[0:3], v[168:171], v[40:43]
	v_mfma_f32_16x16x32_bf16 v[44:47], v[8:11], v[168:171], v[44:47]
	v_mfma_f32_16x16x32_bf16 v[48:51], v[0:3], v[176:179], v[48:51]
	v_mfma_f32_16x16x32_bf16 v[52:55], v[8:11], v[176:179], v[52:55]
	v_mfma_f32_16x16x32_bf16 v[24:27], v[4:7], v[156:159], v[24:27]
	v_mfma_f32_16x16x32_bf16 v[28:31], v[12:15], v[156:159], v[28:31]
	v_mfma_f32_16x16x32_bf16 v[32:35], v[4:7], v[164:167], v[32:35]
	v_mfma_f32_16x16x32_bf16 v[36:39], v[12:15], v[164:167], v[36:39]
	v_mfma_f32_16x16x32_bf16 v[40:43], v[4:7], v[172:175], v[40:43]
	v_mfma_f32_16x16x32_bf16 v[44:47], v[12:15], v[172:175], v[44:47]
	v_mfma_f32_16x16x32_bf16 v[48:51], v[4:7], v[180:183], v[48:51]
	v_mfma_f32_16x16x32_bf16 v[52:55], v[12:15], v[180:183], v[52:55]
	v_mfma_f32_16x16x32_bf16 v[56:59], v[196:199], v[152:155], v[56:59]
	v_mfma_f32_16x16x32_bf16 v[60:63], v[204:207], v[152:155], v[60:63]
	v_mfma_f32_16x16x32_bf16 v[64:67], v[196:199], v[160:163], v[64:67]
	v_mfma_f32_16x16x32_bf16 v[68:71], v[204:207], v[160:163], v[68:71]
	v_mfma_f32_16x16x32_bf16 v[72:75], v[196:199], v[168:171], v[72:75]
	v_mfma_f32_16x16x32_bf16 v[76:79], v[204:207], v[168:171], v[76:79]
	v_mfma_f32_16x16x32_bf16 v[80:83], v[196:199], v[176:179], v[80:83]
	v_mfma_f32_16x16x32_bf16 v[84:87], v[204:207], v[176:179], v[84:87]
	v_mfma_f32_16x16x32_bf16 v[56:59], v[200:203], v[156:159], v[56:59]
	v_mfma_f32_16x16x32_bf16 v[60:63], v[208:211], v[156:159], v[60:63]
	v_mfma_f32_16x16x32_bf16 v[64:67], v[200:203], v[164:167], v[64:67]
	v_mfma_f32_16x16x32_bf16 v[68:71], v[208:211], v[164:167], v[68:71]
	v_mfma_f32_16x16x32_bf16 v[72:75], v[200:203], v[172:175], v[72:75]
	v_mfma_f32_16x16x32_bf16 v[76:79], v[208:211], v[172:175], v[76:79]
	v_mfma_f32_16x16x32_bf16 v[80:83], v[200:203], v[180:183], v[80:83]
	v_mfma_f32_16x16x32_bf16 v[84:87], v[208:211], v[180:183], v[84:87]
	s_setprio 0
	s_barrier
	s_nop 0
	ds_read_b128 v[152:155], v186 offset:16400
	ds_read_b128 v[156:159], v187 offset:16400
	ds_read_b128 v[160:163], v186 offset:18448
	ds_read_b128 v[164:167], v187 offset:18448
	ds_read_b128 v[168:171], v186 offset:20496
	ds_read_b128 v[172:175], v187 offset:20496
	ds_read_b128 v[176:179], v186 offset:22544
	ds_read_b128 v[180:183], v187 offset:22544
	s_cmp_lg_u32 s0, s54
	s_cbranch_scc1 .Lgu_nosw1
	s_mov_b64 s[66:67], s[74:75]
	s_mov_b64 s[70:71], s[80:81]
	s_mov_b64 s[72:73], s[82:83]
.Lgu_nosw1:
	s_add_i32 m0, s39, 0x10000
	s_nop 0
	global_load_lds_dwordx4 v184, s[70:71]
	s_add_i32 m0, s39, 0x10400
	s_nop 0
	global_load_lds_dwordx4 v185, s[70:71]
	s_add_u32 s70, s70, 0x80
	s_addc_u32 s71, s71, 0
	s_add_i32 m0, s39, 0x0
	s_nop 0
	global_load_lds_dwordx4 v184, s[66:67]
	s_add_i32 m0, s39, 0x400
	s_nop 0
	global_load_lds_dwordx4 v185, s[66:67]
	s_add_u32 s66, s66, 0x80
	s_addc_u32 s67, s67, 0
	s_add_i32 m0, s39, 0x14000
	s_nop 0
	global_load_lds_dwordx4 v184, s[72:73]
	s_add_i32 m0, s39, 0x14400
	s_nop 0
	global_load_lds_dwordx4 v185, s[72:73]
	s_add_u32 s72, s72, 0x80
	s_addc_u32 s73, s73, 0
	s_waitcnt lgkmcnt(0)
	s_waitcnt vmcnt(8)
	s_nop 0
	s_barrier
	s_setprio 1
	v_mfma_f32_16x16x32_bf16 v[88:91], v[0:3], v[152:155], v[88:91]
	v_mfma_f32_16x16x32_bf16 v[92:95], v[8:11], v[152:155], v[92:95]
	v_mfma_f32_16x16x32_bf16 v[96:99], v[0:3], v[160:163], v[96:99]
	v_mfma_f32_16x16x32_bf16 v[100:103], v[8:11], v[160:163], v[100:103]
	v_mfma_f32_16x16x32_bf16 v[104:107], v[0:3], v[168:171], v[104:107]
	v_mfma_f32_16x16x32_bf16 v[108:111], v[8:11], v[168:171], v[108:111]
	v_mfma_f32_16x16x32_bf16 v[112:115], v[0:3], v[176:179], v[112:115]
	v_mfma_f32_16x16x32_bf16 v[116:119], v[8:11], v[176:179], v[116:119]
	v_mfma_f32_16x16x32_bf16 v[88:91], v[4:7], v[156:159], v[88:91]
	v_mfma_f32_16x16x32_bf16 v[92:95], v[12:15], v[156:159], v[92:95]
	v_mfma_f32_16x16x32_bf16 v[96:99], v[4:7], v[164:167], v[96:99]
	v_mfma_f32_16x16x32_bf16 v[100:103], v[12:15], v[164:167], v[100:103]
	v_mfma_f32_16x16x32_bf16 v[104:107], v[4:7], v[172:175], v[104:107]
	v_mfma_f32_16x16x32_bf16 v[108:111], v[12:15], v[172:175], v[108:111]
	v_mfma_f32_16x16x32_bf16 v[112:115], v[4:7], v[180:183], v[112:115]
	v_mfma_f32_16x16x32_bf16 v[116:119], v[12:15], v[180:183], v[116:119]
	v_mfma_f32_16x16x32_bf16 v[120:123], v[196:199], v[152:155], v[120:123]
	v_mfma_f32_16x16x32_bf16 v[124:127], v[204:207], v[152:155], v[124:127]
	v_mfma_f32_16x16x32_bf16 v[128:131], v[196:199], v[160:163], v[128:131]
	v_mfma_f32_16x16x32_bf16 v[132:135], v[204:207], v[160:163], v[132:135]
	v_mfma_f32_16x16x32_bf16 v[136:139], v[196:199], v[168:171], v[136:139]
	v_mfma_f32_16x16x32_bf16 v[140:143], v[204:207], v[168:171], v[140:143]
	v_mfma_f32_16x16x32_bf16 v[144:147], v[196:199], v[176:179], v[144:147]
	v_mfma_f32_16x16x32_bf16 v[148:151], v[204:207], v[176:179], v[148:151]
	v_mfma_f32_16x16x32_bf16 v[120:123], v[200:203], v[156:159], v[120:123]
	v_mfma_f32_16x16x32_bf16 v[124:127], v[208:211], v[156:159], v[124:127]
	v_mfma_f32_16x16x32_bf16 v[128:131], v[200:203], v[164:167], v[128:131]
	v_mfma_f32_16x16x32_bf16 v[132:135], v[208:211], v[164:167], v[132:135]
	v_mfma_f32_16x16x32_bf16 v[136:139], v[200:203], v[172:175], v[136:139]
	v_mfma_f32_16x16x32_bf16 v[140:143], v[208:211], v[172:175], v[140:143]
	v_mfma_f32_16x16x32_bf16 v[144:147], v[200:203], v[180:183], v[144:147]
	v_mfma_f32_16x16x32_bf16 v[148:151], v[208:211], v[180:183], v[148:151]
	s_setprio 0
	s_barrier
; #define LAS __attribute__((address_space(3)))
; #define BAR() { __builtin_amdgcn_sched_barrier(0); __builtin_amdgcn_s_barrier(); asm volatile("" ::: "memory"); __builtin_amdgcn_sched_barrier(0); }
; DI void gemm_stream2(const bf16_t* __restrict__ A, int lda, const bf16_t* __restrict__ Bt, int ldb, int K, int m0, int n0, ...
;     ...
; #pragma unroll
;         for (int ks = 0; ks < 2; ++ks) {
;             const unsigned fo = ks ? fo1 : fo0;
;             bf16x8 af[4], bfr[4];
; #pragma unroll
;             for (int i = 0; i < 4; ++i) { af[i] = *(const LAS bf16x8*)(base + aoff + i * 2048 + fo); bfr[i] = *(const LAS bf16x8*)(base + boff + i * 2048 + fo); }
;             if (ks == 1 && more) { if (pf) asm volatile("s_waitcnt vmcnt(3)" ::: "memory"); else asm volatile("s_waitcnt vmcnt(0)" ::: "memory"); }
;             if (pf) { PIECE(s2, ks * 3 + 0); PIECE(s2, ks * 3 + 1); PIECE(s2, ks * 3 + 2); }
;             asm volatile("s_waitcnt lgkmcnt(0)" ::: "memory");
;             BAR();
;             __builtin_amdgcn_s_setprio(1);
; #pragma unroll
;             for (int mi = 0; mi < 4; ++mi)
; #pragma unroll
;                 for (int ni = 0; ni < 4; ++ni) acc[mi][ni] = __builtin_amdgcn_mfma_f32_16x16x32_bf16(bfr[ni], af[mi], acc[mi][ni], 0, 0, 0);
;             __builtin_amdgcn_s_setprio(0);
;             BAR();
;         }
	s_nop 0
	ds_read_b128 v[0:3], v188 offset:32784
	ds_read_b128 v[4:7], v189 offset:32784
	ds_read_b128 v[8:11], v188 offset:34832
	ds_read_b128 v[12:15], v189 offset:34832
	ds_read_b128 v[196:199], v188 offset:49168
	ds_read_b128 v[200:203], v189 offset:49168
	ds_read_b128 v[204:207], v188 offset:51216
	ds_read_b128 v[208:211], v189 offset:51216
	ds_read_b128 v[152:155], v186 offset:32784
	ds_read_b128 v[156:159], v187 offset:32784
	ds_read_b128 v[160:163], v186 offset:34832
	ds_read_b128 v[164:167], v187 offset:34832
	ds_read_b128 v[168:171], v186 offset:36880
	ds_read_b128 v[172:175], v187 offset:36880
	ds_read_b128 v[176:179], v186 offset:38928
	ds_read_b128 v[180:183], v187 offset:38928
	s_cmp_lg_u32 s0, s54
	s_cbranch_scc1 .Lgu_nosw2
	s_mov_b64 s[68:69], s[78:79]
.Lgu_nosw2:
	s_add_i32 m0, s39, 0x4000
	s_nop 0
	global_load_lds_dwordx4 v184, s[68:69]
	s_add_i32 m0, s39, 0x4400
	s_nop 0
	global_load_lds_dwordx4 v185, s[68:69]
	s_add_u32 s68, s68, 0x80
	s_addc_u32 s69, s69, 0
	s_waitcnt lgkmcnt(0)
	s_waitcnt vmcnt(8)
	s_nop 0
	s_barrier
	s_setprio 1
	v_mfma_f32_16x16x32_bf16 v[24:27], v[0:3], v[152:155], v[24:27]
	v_mfma_f32_16x16x32_bf16 v[28:31], v[8:11], v[152:155], v[28:31]
	v_mfma_f32_16x16x32_bf16 v[32:35], v[0:3], v[160:163], v[32:35]
	v_mfma_f32_16x16x32_bf16 v[36:39], v[8:11], v[160:163], v[36:39]
	v_mfma_f32_16x16x32_bf16 v[40:43], v[0:3], v[168:171], v[40:43]
	v_mfma_f32_16x16x32_bf16 v[44:47], v[8:11], v[168:171], v[44:47]
	v_mfma_f32_16x16x32_bf16 v[48:51], v[0:3], v[176:179], v[48:51]
	v_mfma_f32_16x16x32_bf16 v[52:55], v[8:11], v[176:179], v[52:55]
	v_mfma_f32_16x16x32_bf16 v[24:27], v[4:7], v[156:159], v[24:27]
	v_mfma_f32_16x16x32_bf16 v[28:31], v[12:15], v[156:159], v[28:31]
	v_mfma_f32_16x16x32_bf16 v[32:35], v[4:7], v[164:167], v[32:35]
	v_mfma_f32_16x16x32_bf16 v[36:39], v[12:15], v[164:167], v[36:39]
	v_mfma_f32_16x16x32_bf16 v[40:43], v[4:7], v[172:175], v[40:43]
	v_mfma_f32_16x16x32_bf16 v[44:47], v[12:15], v[172:175], v[44:47]
	v_mfma_f32_16x16x32_bf16 v[48:51], v[4:7], v[180:183], v[48:51]
	v_mfma_f32_16x16x32_bf16 v[52:55], v[12:15], v[180:183], v[52:55]
	v_mfma_f32_16x16x32_bf16 v[56:59], v[196:199], v[152:155], v[56:59]
	v_mfma_f32_16x16x32_bf16 v[60:63], v[204:207], v[152:155], v[60:63]
	v_mfma_f32_16x16x32_bf16 v[64:67], v[196:199], v[160:163], v[64:67]
	v_mfma_f32_16x16x32_bf16 v[68:71], v[204:207], v[160:163], v[68:71]
	v_mfma_f32_16x16x32_bf16 v[72:75], v[196:199], v[168:171], v[72:75]
	v_mfma_f32_16x16x32_bf16 v[76:79], v[204:207], v[168:171], v[76:79]
	v_mfma_f32_16x16x32_bf16 v[80:83], v[196:199], v[176:179], v[80:83]
	v_mfma_f32_16x16x32_bf16 v[84:87], v[204:207], v[176:179], v[84:87]
	v_mfma_f32_16x16x32_bf16 v[56:59], v[200:203], v[156:159], v[56:59]
	v_mfma_f32_16x16x32_bf16 v[60:63], v[208:211], v[156:159], v[60:63]
	v_mfma_f32_16x16x32_bf16 v[64:67], v[200:203], v[164:167], v[64:67]
	v_mfma_f32_16x16x32_bf16 v[68:71], v[208:211], v[164:167], v[68:71]
	v_mfma_f32_16x16x32_bf16 v[72:75], v[200:203], v[172:175], v[72:75]
	v_mfma_f32_16x16x32_bf16 v[76:79], v[208:211], v[172:175], v[76:79]
	v_mfma_f32_16x16x32_bf16 v[80:83], v[200:203], v[180:183], v[80:83]
	v_mfma_f32_16x16x32_bf16 v[84:87], v[208:211], v[180:183], v[84:87]
	s_setprio 0
	s_barrier
	s_nop 0
	ds_read_b128 v[152:155], v186 offset:49168
	ds_read_b128 v[156:159], v187 offset:49168
	ds_read_b128 v[160:163], v186 offset:51216
	ds_read_b128 v[164:167], v187 offset:51216
	ds_read_b128 v[168:171], v186 offset:53264
	ds_read_b128 v[172:175], v187 offset:53264
	ds_read_b128 v[176:179], v186 offset:55312
	ds_read_b128 v[180:183], v187 offset:55312
	s_add_i32 m0, s39, 0x18000
	s_nop 0
	global_load_lds_dwordx4 v184, s[70:71]
	s_add_i32 m0, s39, 0x18400
	s_nop 0
	global_load_lds_dwordx4 v185, s[70:71]
	s_add_u32 s70, s70, 0x80
	s_addc_u32 s71, s71, 0
	s_add_i32 m0, s39, 0x8000
	s_nop 0
	global_load_lds_dwordx4 v184, s[66:67]
	s_add_i32 m0, s39, 0x8400
	s_nop 0
	global_load_lds_dwordx4 v185, s[66:67]
	s_add_u32 s66, s66, 0x80
	s_addc_u32 s67, s67, 0
	s_add_i32 m0, s39, 0x1c000
	s_nop 0
	global_load_lds_dwordx4 v184, s[72:73]
	s_add_i32 m0, s39, 0x1c400
	s_nop 0
	global_load_lds_dwordx4 v185, s[72:73]
	s_add_u32 s72, s72, 0x80
	s_addc_u32 s73, s73, 0
	s_waitcnt lgkmcnt(0)
	s_waitcnt vmcnt(8)
	s_barrier
	s_setprio 1
	v_mfma_f32_16x16x32_bf16 v[88:91], v[0:3], v[152:155], v[88:91]
	v_mfma_f32_16x16x32_bf16 v[92:95], v[8:11], v[152:155], v[92:95]
	v_mfma_f32_16x16x32_bf16 v[96:99], v[0:3], v[160:163], v[96:99]
	v_mfma_f32_16x16x32_bf16 v[100:103], v[8:11], v[160:163], v[100:103]
	v_mfma_f32_16x16x32_bf16 v[104:107], v[0:3], v[168:171], v[104:107]
	v_mfma_f32_16x16x32_bf16 v[108:111], v[8:11], v[168:171], v[108:111]
	v_mfma_f32_16x16x32_bf16 v[112:115], v[0:3], v[176:179], v[112:115]
	v_mfma_f32_16x16x32_bf16 v[116:119], v[8:11], v[176:179], v[116:119]
	v_mfma_f32_16x16x32_bf16 v[88:91], v[4:7], v[156:159], v[88:91]
	v_mfma_f32_16x16x32_bf16 v[92:95], v[12:15], v[156:159], v[92:95]
	v_mfma_f32_16x16x32_bf16 v[96:99], v[4:7], v[164:167], v[96:99]
	v_mfma_f32_16x16x32_bf16 v[100:103], v[12:15], v[164:167], v[100:103]
	v_mfma_f32_16x16x32_bf16 v[104:107], v[4:7], v[172:175], v[104:107]
	v_mfma_f32_16x16x32_bf16 v[108:111], v[12:15], v[172:175], v[108:111]
	v_mfma_f32_16x16x32_bf16 v[112:115], v[4:7], v[180:183], v[112:115]
	v_mfma_f32_16x16x32_bf16 v[116:119], v[12:15], v[180:183], v[116:119]
	v_mfma_f32_16x16x32_bf16 v[120:123], v[196:199], v[152:155], v[120:123]
	v_mfma_f32_16x16x32_bf16 v[124:127], v[204:207], v[152:155], v[124:127]
	v_mfma_f32_16x16x32_bf16 v[128:131], v[196:199], v[160:163], v[128:131]
	v_mfma_f32_16x16x32_bf16 v[132:135], v[204:207], v[160:163], v[132:135]
	v_mfma_f32_16x16x32_bf16 v[136:139], v[196:199], v[168:171], v[136:139]
	v_mfma_f32_16x16x32_bf16 v[140:143], v[204:207], v[168:171], v[140:143]
	v_mfma_f32_16x16x32_bf16 v[144:147], v[196:199], v[176:179], v[144:147]
	v_mfma_f32_16x16x32_bf16 v[148:151], v[204:207], v[176:179], v[148:151]
	v_mfma_f32_16x16x32_bf16 v[120:123], v[200:203], v[156:159], v[120:123]
	v_mfma_f32_16x16x32_bf16 v[124:127], v[208:211], v[156:159], v[124:127]
	v_mfma_f32_16x16x32_bf16 v[128:131], v[200:203], v[164:167], v[128:131]
	v_mfma_f32_16x16x32_bf16 v[132:135], v[208:211], v[164:167], v[132:135]
	v_mfma_f32_16x16x32_bf16 v[136:139], v[200:203], v[172:175], v[136:139]
	v_mfma_f32_16x16x32_bf16 v[140:143], v[208:211], v[172:175], v[140:143]
	v_mfma_f32_16x16x32_bf16 v[144:147], v[200:203], v[180:183], v[144:147]
	v_mfma_f32_16x16x32_bf16 v[148:151], v[208:211], v[180:183], v[148:151]
	s_setprio 0
	s_barrier
; #define LAS __attribute__((address_space(3)))
; #define BAR() { __builtin_amdgcn_sched_barrier(0); __builtin_amdgcn_s_barrier(); asm volatile("" ::: "memory"); __builtin_amdgcn_sched_barrier(0); }
; DI void gemm_stream2(const bf16_t* __restrict__ A, int lda, const bf16_t* __restrict__ Bt, int ldb, int K, int m0, int n0, ...
;     ...
;     for (int kt = 0; kt < nk; ++kt) {
;         const bool pf = (kt + 2 < nk) || has_next, more = (kt + 1 < nk) || has_next;
;         const bf16_t* pa = (kt + 2 < nk) ? ga + (kt + 2) * 64 : gan + (kt + 2 - nk) * 64;
;         const bf16_t* pb = (kt + 2 < nk) ? gb + (kt + 2) * 64 : gbn + (kt + 2 - nk) * 64;
;         const int plda = (kt + 2 < nk) ? lda : ldan, pldb = (kt + 2 < nk) ? ldb : ldbn;
;         const int s2 = st >= 1 ? st - 1 : 2;
;         const LAS char* base = lds + st * 49152;
; #pragma unroll
;         for (int ks = 0; ks < 2; ++ks) {
;             const unsigned fo = ks ? fo1 : fo0;
;             bf16x8 af[4], bfr[4];
; #pragma unroll
;             for (int i = 0; i < 4; ++i) { af[i] = *(const LAS bf16x8*)(base + aoff + i * 2048 + fo); bfr[i] = *(const LAS bf16x8*)(base + boff + i * 2048 + fo); }
;             if (ks == 1 && more) { if (pf) asm volatile("s_waitcnt vmcnt(3)" ::: "memory"); else asm volatile("s_waitcnt vmcnt(0)" ::: "memory"); }
;             if (pf) { PIECE(s2, ks * 3 + 0); PIECE(s2, ks * 3 + 1); PIECE(s2, ks * 3 + 2); }
;             asm volatile("s_waitcnt lgkmcnt(0)" ::: "memory");
;             BAR();
;             __builtin_amdgcn_s_setprio(1);
; #pragma unroll
;             for (int mi = 0; mi < 4; ++mi)
; #pragma unroll
;                 for (int ni = 0; ni < 4; ++ni) acc[mi][ni] = __builtin_amdgcn_mfma_f32_16x16x32_bf16(bfr[ni], af[mi], acc[mi][ni], 0, 0, 0);
;             __builtin_amdgcn_s_setprio(0);
;             BAR();
;         }
;         st = st == 2 ? 0 : st + 1;
;     }
	s_nop 0
	s_sub_u32 s0, s0, 1
	s_cmp_lg_u32 s0, 0
	s_cbranch_scc1 .Lgu_kloop
	s_cmp_lg_u32 s54, 0
	s_cbranch_scc1 .Lgu_epi
	ds_read_b128 v[0:3], v188 offset:16
	ds_read_b128 v[4:7], v189 offset:16
	ds_read_b128 v[8:11], v188 offset:2064
	ds_read_b128 v[12:15], v189 offset:2064
	ds_read_b128 v[196:199], v188 offset:16400
	ds_read_b128 v[200:203], v189 offset:16400
	ds_read_b128 v[204:207], v188 offset:18448
	ds_read_b128 v[208:211], v189 offset:18448
	ds_read_b128 v[152:155], v186 offset:16
	ds_read_b128 v[156:159], v187 offset:16
	ds_read_b128 v[160:163], v186 offset:2064
	ds_read_b128 v[164:167], v187 offset:2064
	ds_read_b128 v[168:171], v186 offset:4112
	ds_read_b128 v[172:175], v187 offset:4112
	ds_read_b128 v[176:179], v186 offset:6160
	ds_read_b128 v[180:183], v187 offset:6160
	s_add_i32 m0, s39, 0xc000
	s_nop 0
	global_load_lds_dwordx4 v184, s[68:69]
	s_add_i32 m0, s39, 0xc400
	s_nop 0
	global_load_lds_dwordx4 v185, s[68:69]
	s_add_u32 s68, s68, 0x80
	s_addc_u32 s69, s69, 0
	s_waitcnt lgkmcnt(0)
	s_waitcnt vmcnt(8)
	s_barrier
	s_setprio 1
	v_mfma_f32_16x16x32_bf16 v[24:27], v[0:3], v[152:155], v[24:27]
	v_mfma_f32_16x16x32_bf16 v[28:31], v[8:11], v[152:155], v[28:31]
	v_mfma_f32_16x16x32_bf16 v[32:35], v[0:3], v[160:163], v[32:35]
	v_mfma_f32_16x16x32_bf16 v[36:39], v[8:11], v[160:163], v[36:39]
	v_mfma_f32_16x16x32_bf16 v[40:43], v[0:3], v[168:171], v[40:43]
	v_mfma_f32_16x16x32_bf16 v[44:47], v[8:11], v[168:171], v[44:47]
	v_mfma_f32_16x16x32_bf16 v[48:51], v[0:3], v[176:179], v[48:51]
	v_mfma_f32_16x16x32_bf16 v[52:55], v[8:11], v[176:179], v[52:55]
	v_mfma_f32_16x16x32_bf16 v[24:27], v[4:7], v[156:159], v[24:27]
	v_mfma_f32_16x16x32_bf16 v[28:31], v[12:15], v[156:159], v[28:31]
	v_mfma_f32_16x16x32_bf16 v[32:35], v[4:7], v[164:167], v[32:35]
	v_mfma_f32_16x16x32_bf16 v[36:39], v[12:15], v[164:167], v[36:39]
	v_mfma_f32_16x16x32_bf16 v[40:43], v[4:7], v[172:175], v[40:43]
	v_mfma_f32_16x16x32_bf16 v[44:47], v[12:15], v[172:175], v[44:47]
	v_mfma_f32_16x16x32_bf16 v[48:51], v[4:7], v[180:183], v[48:51]
	v_mfma_f32_16x16x32_bf16 v[52:55], v[12:15], v[180:183], v[52:55]
	v_mfma_f32_16x16x32_bf16 v[56:59], v[196:199], v[152:155], v[56:59]
	v_mfma_f32_16x16x32_bf16 v[60:63], v[204:207], v[152:155], v[60:63]
	v_mfma_f32_16x16x32_bf16 v[64:67], v[196:199], v[160:163], v[64:67]
	v_mfma_f32_16x16x32_bf16 v[68:71], v[204:207], v[160:163], v[68:71]
	v_mfma_f32_16x16x32_bf16 v[72:75], v[196:199], v[168:171], v[72:75]
	v_mfma_f32_16x16x32_bf16 v[76:79], v[204:207], v[168:171], v[76:79]
	v_mfma_f32_16x16x32_bf16 v[80:83], v[196:199], v[176:179], v[80:83]
	v_mfma_f32_16x16x32_bf16 v[84:87], v[204:207], v[176:179], v[84:87]
	v_mfma_f32_16x16x32_bf16 v[56:59], v[200:203], v[156:159], v[56:59]
	v_mfma_f32_16x16x32_bf16 v[60:63], v[208:211], v[156:159], v[60:63]
	v_mfma_f32_16x16x32_bf16 v[64:67], v[200:203], v[164:167], v[64:67]
	v_mfma_f32_16x16x32_bf16 v[68:71], v[208:211], v[164:167], v[68:71]
	v_mfma_f32_16x16x32_bf16 v[72:75], v[200:203], v[172:175], v[72:75]
	v_mfma_f32_16x16x32_bf16 v[76:79], v[208:211], v[172:175], v[76:79]
	v_mfma_f32_16x16x32_bf16 v[80:83], v[200:203], v[180:183], v[80:83]
	v_mfma_f32_16x16x32_bf16 v[84:87], v[208:211], v[180:183], v[84:87]
	s_setprio 0
	s_barrier
	ds_read_b128 v[152:155], v186 offset:16400
	ds_read_b128 v[156:159], v187 offset:16400
	ds_read_b128 v[160:163], v186 offset:18448
	ds_read_b128 v[164:167], v187 offset:18448
	ds_read_b128 v[168:171], v186 offset:20496
	ds_read_b128 v[172:175], v187 offset:20496
	ds_read_b128 v[176:179], v186 offset:22544
	ds_read_b128 v[180:183], v187 offset:22544
	s_waitcnt lgkmcnt(0)
	s_waitcnt vmcnt(2)
	s_barrier
	s_setprio 1
	v_mfma_f32_16x16x32_bf16 v[88:91], v[0:3], v[152:155], v[88:91]
	v_mfma_f32_16x16x32_bf16 v[92:95], v[8:11], v[152:155], v[92:95]
	v_mfma_f32_16x16x32_bf16 v[96:99], v[0:3], v[160:163], v[96:99]
	v_mfma_f32_16x16x32_bf16 v[100:103], v[8:11], v[160:163], v[100:103]
	v_mfma_f32_16x16x32_bf16 v[104:107], v[0:3], v[168:171], v[104:107]
	v_mfma_f32_16x16x32_bf16 v[108:111], v[8:11], v[168:171], v[108:111]
	v_mfma_f32_16x16x32_bf16 v[112:115], v[0:3], v[176:179], v[112:115]
	v_mfma_f32_16x16x32_bf16 v[116:119], v[8:11], v[176:179], v[116:119]
	v_mfma_f32_16x16x32_bf16 v[88:91], v[4:7], v[156:159], v[88:91]
	v_mfma_f32_16x16x32_bf16 v[92:95], v[12:15], v[156:159], v[92:95]
	v_mfma_f32_16x16x32_bf16 v[96:99], v[4:7], v[164:167], v[96:99]
	v_mfma_f32_16x16x32_bf16 v[100:103], v[12:15], v[164:167], v[100:103]
	v_mfma_f32_16x16x32_bf16 v[104:107], v[4:7], v[172:175], v[104:107]
	v_mfma_f32_16x16x32_bf16 v[108:111], v[12:15], v[172:175], v[108:111]
	v_mfma_f32_16x16x32_bf16 v[112:115], v[4:7], v[180:183], v[112:115]
	v_mfma_f32_16x16x32_bf16 v[116:119], v[12:15], v[180:183], v[116:119]
	v_mfma_f32_16x16x32_bf16 v[120:123], v[196:199], v[152:155], v[120:123]
	v_mfma_f32_16x16x32_bf16 v[124:127], v[204:207], v[152:155], v[124:127]
	v_mfma_f32_16x16x32_bf16 v[128:131], v[196:199], v[160:163], v[128:131]
	v_mfma_f32_16x16x32_bf16 v[132:135], v[204:207], v[160:163], v[132:135]
	v_mfma_f32_16x16x32_bf16 v[136:139], v[196:199], v[168:171], v[136:139]
	v_mfma_f32_16x16x32_bf16 v[140:143], v[204:207], v[168:171], v[140:143]
	v_mfma_f32_16x16x32_bf16 v[144:147], v[196:199], v[176:179], v[144:147]
	v_mfma_f32_16x16x32_bf16 v[148:151], v[204:207], v[176:179], v[148:151]
	v_mfma_f32_16x16x32_bf16 v[120:123], v[200:203], v[156:159], v[120:123]
	v_mfma_f32_16x16x32_bf16 v[124:127], v[208:211], v[156:159], v[124:127]
	v_mfma_f32_16x16x32_bf16 v[128:131], v[200:203], v[164:167], v[128:131]
	v_mfma_f32_16x16x32_bf16 v[132:135], v[208:211], v[164:167], v[132:135]
	v_mfma_f32_16x16x32_bf16 v[136:139], v[200:203], v[172:175], v[136:139]
	v_mfma_f32_16x16x32_bf16 v[140:143], v[208:211], v[172:175], v[140:143]
	v_mfma_f32_16x16x32_bf16 v[144:147], v[200:203], v[180:183], v[144:147]
	v_mfma_f32_16x16x32_bf16 v[148:151], v[208:211], v[180:183], v[148:151]
	s_setprio 0
	s_barrier
; #define LAS __attribute__((address_space(3)))
; #define BAR() { __builtin_amdgcn_sched_barrier(0); __builtin_amdgcn_s_barrier(); asm volatile("" ::: "memory"); __builtin_amdgcn_sched_barrier(0); }
; DI void gemm_stream2(const bf16_t* __restrict__ A, int lda, const bf16_t* __restrict__ Bt, int ldb, int K, int m0, int n0, ...
;     ...
;     for (int kt = 0; kt < nk; ++kt) {
;         const bool pf = (kt + 2 < nk) || has_next, more = (kt + 1 < nk) || has_next;
;         const bf16_t* pa = (kt + 2 < nk) ? ga + (kt + 2) * 64 : gan + (kt + 2 - nk) * 64;
;         const bf16_t* pb = (kt + 2 < nk) ? gb + (kt + 2) * 64 : gbn + (kt + 2 - nk) * 64;
;         const int plda = (kt + 2 < nk) ? lda : ldan, pldb = (kt + 2 < nk) ? ldb : ldbn;
;         const int s2 = st >= 1 ? st - 1 : 2;
;         const LAS char* base = lds + st * 49152;
; #pragma unroll
;         for (int ks = 0; ks < 2; ++ks) {
;             const unsigned fo = ks ? fo1 : fo0;
;             bf16x8 af[4], bfr[4];
; #pragma unroll
;             for (int i = 0; i < 4; ++i) { af[i] = *(const LAS bf16x8*)(base + aoff + i * 2048 + fo); bfr[i] = *(const LAS bf16x8*)(base + boff + i * 2048 + fo); }
;             if (ks == 1 && more) { if (pf) asm volatile("s_waitcnt vmcnt(3)" ::: "memory"); else asm volatile("s_waitcnt vmcnt(0)" ::: "memory"); }
;             if (pf) { PIECE(s2, ks * 3 + 0); PIECE(s2, ks * 3 + 1); PIECE(s2, ks * 3 + 2); }
;             asm volatile("s_waitcnt lgkmcnt(0)" ::: "memory");
;             BAR();
;             __builtin_amdgcn_s_setprio(1);
; #pragma unroll
;             for (int mi = 0; mi < 4; ++mi)
; #pragma unroll
;                 for (int ni = 0; ni < 4; ++ni) acc[mi][ni] = __builtin_amdgcn_mfma_f32_16x16x32_bf16(bfr[ni], af[mi], acc[mi][ni], 0, 0, 0);
;             __builtin_amdgcn_s_setprio(0);
;             BAR();
;         }
;         st = st == 2 ? 0 : st + 1;
;     }
;     if (grp == 0) BAR();
	ds_read_b128 v[0:3], v188 offset:32784
	ds_read_b128 v[4:7], v189 offset:32784
	ds_read_b128 v[8:11], v188 offset:34832
	ds_read_b128 v[12:15], v189 offset:34832
	ds_read_b128 v[196:199], v188 offset:49168
	ds_read_b128 v[200:203], v189 offset:49168
	ds_read_b128 v[204:207], v188 offset:51216
	ds_read_b128 v[208:211], v189 offset:51216
	ds_read_b128 v[152:155], v186 offset:32784
	ds_read_b128 v[156:159], v187 offset:32784
	ds_read_b128 v[160:163], v186 offset:34832
	ds_read_b128 v[164:167], v187 offset:34832
	ds_read_b128 v[168:171], v186 offset:36880
	ds_read_b128 v[172:175], v187 offset:36880
	ds_read_b128 v[176:179], v186 offset:38928
	ds_read_b128 v[180:183], v187 offset:38928
	s_waitcnt lgkmcnt(0)
	s_waitcnt vmcnt(0)
	s_barrier
	s_setprio 1
	v_mfma_f32_16x16x32_bf16 v[24:27], v[0:3], v[152:155], v[24:27]
	v_mfma_f32_16x16x32_bf16 v[28:31], v[8:11], v[152:155], v[28:31]
	v_mfma_f32_16x16x32_bf16 v[32:35], v[0:3], v[160:163], v[32:35]
	v_mfma_f32_16x16x32_bf16 v[36:39], v[8:11], v[160:163], v[36:39]
	v_mfma_f32_16x16x32_bf16 v[40:43], v[0:3], v[168:171], v[40:43]
	v_mfma_f32_16x16x32_bf16 v[44:47], v[8:11], v[168:171], v[44:47]
	v_mfma_f32_16x16x32_bf16 v[48:51], v[0:3], v[176:179], v[48:51]
	v_mfma_f32_16x16x32_bf16 v[52:55], v[8:11], v[176:179], v[52:55]
	v_mfma_f32_16x16x32_bf16 v[24:27], v[4:7], v[156:159], v[24:27]
	v_mfma_f32_16x16x32_bf16 v[28:31], v[12:15], v[156:159], v[28:31]
	v_mfma_f32_16x16x32_bf16 v[32:35], v[4:7], v[164:167], v[32:35]
	v_mfma_f32_16x16x32_bf16 v[36:39], v[12:15], v[164:167], v[36:39]
	v_mfma_f32_16x16x32_bf16 v[40:43], v[4:7], v[172:175], v[40:43]
	v_mfma_f32_16x16x32_bf16 v[44:47], v[12:15], v[172:175], v[44:47]
	v_mfma_f32_16x16x32_bf16 v[48:51], v[4:7], v[180:183], v[48:51]
	v_mfma_f32_16x16x32_bf16 v[52:55], v[12:15], v[180:183], v[52:55]
	v_mfma_f32_16x16x32_bf16 v[56:59], v[196:199], v[152:155], v[56:59]
	v_mfma_f32_16x16x32_bf16 v[60:63], v[204:207], v[152:155], v[60:63]
	v_mfma_f32_16x16x32_bf16 v[64:67], v[196:199], v[160:163], v[64:67]
	v_mfma_f32_16x16x32_bf16 v[68:71], v[204:207], v[160:163], v[68:71]
	v_mfma_f32_16x16x32_bf16 v[72:75], v[196:199], v[168:171], v[72:75]
	v_mfma_f32_16x16x32_bf16 v[76:79], v[204:207], v[168:171], v[76:79]
	v_mfma_f32_16x16x32_bf16 v[80:83], v[196:199], v[176:179], v[80:83]
	v_mfma_f32_16x16x32_bf16 v[84:87], v[204:207], v[176:179], v[84:87]
	v_mfma_f32_16x16x32_bf16 v[56:59], v[200:203], v[156:159], v[56:59]
	v_mfma_f32_16x16x32_bf16 v[60:63], v[208:211], v[156:159], v[60:63]
	v_mfma_f32_16x16x32_bf16 v[64:67], v[200:203], v[164:167], v[64:67]
	v_mfma_f32_16x16x32_bf16 v[68:71], v[208:211], v[164:167], v[68:71]
	v_mfma_f32_16x16x32_bf16 v[72:75], v[200:203], v[172:175], v[72:75]
	v_mfma_f32_16x16x32_bf16 v[76:79], v[208:211], v[172:175], v[76:79]
	v_mfma_f32_16x16x32_bf16 v[80:83], v[200:203], v[180:183], v[80:83]
	v_mfma_f32_16x16x32_bf16 v[84:87], v[208:211], v[180:183], v[84:87]
	s_setprio 0
	s_barrier
	ds_read_b128 v[152:155], v186 offset:49168
	ds_read_b128 v[156:159], v187 offset:49168
	ds_read_b128 v[160:163], v186 offset:51216
	ds_read_b128 v[164:167], v187 offset:51216
	ds_read_b128 v[168:171], v186 offset:53264
	ds_read_b128 v[172:175], v187 offset:53264
	ds_read_b128 v[176:179], v186 offset:55312
	ds_read_b128 v[180:183], v187 offset:55312
	s_waitcnt lgkmcnt(0)
	s_barrier
	s_setprio 1
	v_mfma_f32_16x16x32_bf16 v[88:91], v[0:3], v[152:155], v[88:91]
	v_mfma_f32_16x16x32_bf16 v[92:95], v[8:11], v[152:155], v[92:95]
	v_mfma_f32_16x16x32_bf16 v[96:99], v[0:3], v[160:163], v[96:99]
	v_mfma_f32_16x16x32_bf16 v[100:103], v[8:11], v[160:163], v[100:103]
	v_mfma_f32_16x16x32_bf16 v[104:107], v[0:3], v[168:171], v[104:107]
	v_mfma_f32_16x16x32_bf16 v[108:111], v[8:11], v[168:171], v[108:111]
	v_mfma_f32_16x16x32_bf16 v[112:115], v[0:3], v[176:179], v[112:115]
	v_mfma_f32_16x16x32_bf16 v[116:119], v[8:11], v[176:179], v[116:119]
	v_mfma_f32_16x16x32_bf16 v[88:91], v[4:7], v[156:159], v[88:91]
	v_mfma_f32_16x16x32_bf16 v[92:95], v[12:15], v[156:159], v[92:95]
	v_mfma_f32_16x16x32_bf16 v[96:99], v[4:7], v[164:167], v[96:99]
	v_mfma_f32_16x16x32_bf16 v[100:103], v[12:15], v[164:167], v[100:103]
	v_mfma_f32_16x16x32_bf16 v[104:107], v[4:7], v[172:175], v[104:107]
	v_mfma_f32_16x16x32_bf16 v[108:111], v[12:15], v[172:175], v[108:111]
	v_mfma_f32_16x16x32_bf16 v[112:115], v[4:7], v[180:183], v[112:115]
	v_mfma_f32_16x16x32_bf16 v[116:119], v[12:15], v[180:183], v[116:119]
	v_mfma_f32_16x16x32_bf16 v[120:123], v[196:199], v[152:155], v[120:123]
	v_mfma_f32_16x16x32_bf16 v[124:127], v[204:207], v[152:155], v[124:127]
	v_mfma_f32_16x16x32_bf16 v[128:131], v[196:199], v[160:163], v[128:131]
	v_mfma_f32_16x16x32_bf16 v[132:135], v[204:207], v[160:163], v[132:135]
	v_mfma_f32_16x16x32_bf16 v[136:139], v[196:199], v[168:171], v[136:139]
	v_mfma_f32_16x16x32_bf16 v[140:143], v[204:207], v[168:171], v[140:143]
	v_mfma_f32_16x16x32_bf16 v[144:147], v[196:199], v[176:179], v[144:147]
	v_mfma_f32_16x16x32_bf16 v[148:151], v[204:207], v[176:179], v[148:151]
	v_mfma_f32_16x16x32_bf16 v[120:123], v[200:203], v[156:159], v[120:123]
	v_mfma_f32_16x16x32_bf16 v[124:127], v[208:211], v[156:159], v[124:127]
	v_mfma_f32_16x16x32_bf16 v[128:131], v[200:203], v[164:167], v[128:131]
	v_mfma_f32_16x16x32_bf16 v[132:135], v[208:211], v[164:167], v[132:135]
	v_mfma_f32_16x16x32_bf16 v[136:139], v[200:203], v[172:175], v[136:139]
	v_mfma_f32_16x16x32_bf16 v[140:143], v[208:211], v[172:175], v[140:143]
	v_mfma_f32_16x16x32_bf16 v[144:147], v[200:203], v[180:183], v[144:147]
	v_mfma_f32_16x16x32_bf16 v[148:151], v[208:211], v[180:183], v[148:151]
	s_setprio 0
	s_barrier
	s_cmp_lg_u32 s33, 0
	s_cbranch_scc1 .Lgu_epi
	s_barrier

; #define LAS __attribute__((address_space(3)))
; #define BAR() { __builtin_amdgcn_sched_barrier(0); __builtin_amdgcn_s_barrier(); asm volatile("" ::: "memory"); __builtin_amdgcn_sched_barrier(0); }
; DI void gemm_stream2(const bf16_t* __restrict__ A, int lda, const bf16_t* __restrict__ Bt, int ldb, int K, int m0, int n0, ...
;     ...
;     for (int kt = 0; kt < nk; ++kt) {
;         const bool pf = (kt + 2 < nk) || has_next, more = (kt + 1 < nk) || has_next;
;         const bf16_t* pa = (kt + 2 < nk) ? ga + (kt + 2) * 64 : gan + (kt + 2 - nk) * 64;
;         const bf16_t* pb = (kt + 2 < nk) ? gb + (kt + 2) * 64 : gbn + (kt + 2 - nk) * 64;
;         const int plda = (kt + 2 < nk) ? lda : ldan, pldb = (kt + 2 < nk) ? ldb : ldbn;
;         const int s2 = st >= 1 ? st - 1 : 2;
;         const LAS char* base = lds + st * 49152;
; #pragma unroll
;         for (int ks = 0; ks < 2; ++ks) {
;             const unsigned fo = ks ? fo1 : fo0;
;             bf16x8 af[4], bfr[4];
; #pragma unroll
;             for (int i = 0; i < 4; ++i) { af[i] = *(const LAS bf16x8*)(base + aoff + i * 2048 + fo); bfr[i] = *(const LAS bf16x8*)(base + boff + i * 2048 + fo); }
;             if (ks == 1 && more) { if (pf) asm volatile("s_waitcnt vmcnt(3)" ::: "memory"); else asm volatile("s_waitcnt vmcnt(0)" ::: "memory"); }
;             if (pf) { PIECE(s2, ks * 3 + 0); PIECE(s2, ks * 3 + 1); PIECE(s2, ks * 3 + 2); }
;             asm volatile("s_waitcnt lgkmcnt(0)" ::: "memory");
;             BAR();
;             __builtin_amdgcn_s_setprio(1);
; #pragma unroll
;             for (int mi = 0; mi < 4; ++mi)
; #pragma unroll
;                 for (int ni = 0; ni < 4; ++ni) acc[mi][ni] = __builtin_amdgcn_mfma_f32_16x16x32_bf16(bfr[ni], af[mi], acc[mi][ni], 0, 0, 0);
;             __builtin_amdgcn_s_setprio(0);
;             BAR();
;         }
;         st = st == 2 ? 0 : st + 1;
;     }
.Lgyd_nosw2:
	s_add_i32 m0, s39, 0x4000
	s_nop 0
	global_load_lds_dwordx4 v184, s[68:69]
	s_add_i32 m0, s39, 0x4400
	s_nop 0
	global_load_lds_dwordx4 v185, s[68:69]
	s_add_u32 s68, s68, 0x80
	s_addc_u32 s69, s69, 0
	s_waitcnt lgkmcnt(0)
	s_waitcnt vmcnt(8)
	s_nop 0
	s_barrier
	s_setprio 1
	v_mfma_f32_16x16x32_bf16 v[24:27], v[0:3], v[152:155], v[24:27]
	v_mfma_f32_16x16x32_bf16 v[28:31], v[8:11], v[152:155], v[28:31]
	v_mfma_f32_16x16x32_bf16 v[32:35], v[0:3], v[160:163], v[32:35]
	v_mfma_f32_16x16x32_bf16 v[36:39], v[8:11], v[160:163], v[36:39]
	v_mfma_f32_16x16x32_bf16 v[40:43], v[0:3], v[168:171], v[40:43]
	v_mfma_f32_16x16x32_bf16 v[44:47], v[8:11], v[168:171], v[44:47]
	v_mfma_f32_16x16x32_bf16 v[48:51], v[0:3], v[176:179], v[48:51]
	v_mfma_f32_16x16x32_bf16 v[52:55], v[8:11], v[176:179], v[52:55]
	v_mfma_f32_16x16x32_bf16 v[24:27], v[4:7], v[156:159], v[24:27]
	v_mfma_f32_16x16x32_bf16 v[28:31], v[12:15], v[156:159], v[28:31]
	v_mfma_f32_16x16x32_bf16 v[32:35], v[4:7], v[164:167], v[32:35]
	v_mfma_f32_16x16x32_bf16 v[36:39], v[12:15], v[164:167], v[36:39]
	v_mfma_f32_16x16x32_bf16 v[40:43], v[4:7], v[172:175], v[40:43]
	v_mfma_f32_16x16x32_bf16 v[44:47], v[12:15], v[172:175], v[44:47]
	v_mfma_f32_16x16x32_bf16 v[48:51], v[4:7], v[180:183], v[48:51]
	v_mfma_f32_16x16x32_bf16 v[52:55], v[12:15], v[180:183], v[52:55]
	v_mfma_f32_16x16x32_bf16 v[56:59], v[196:199], v[152:155], v[56:59]
	v_mfma_f32_16x16x32_bf16 v[60:63], v[204:207], v[152:155], v[60:63]
	v_mfma_f32_16x16x32_bf16 v[64:67], v[196:199], v[160:163], v[64:67]
	v_mfma_f32_16x16x32_bf16 v[68:71], v[204:207], v[160:163], v[68:71]
	v_mfma_f32_16x16x32_bf16 v[72:75], v[196:199], v[168:171], v[72:75]
	v_mfma_f32_16x16x32_bf16 v[76:79], v[204:207], v[168:171], v[76:79]
	v_mfma_f32_16x16x32_bf16 v[80:83], v[196:199], v[176:179], v[80:83]
	v_mfma_f32_16x16x32_bf16 v[84:87], v[204:207], v[176:179], v[84:87]
	v_mfma_f32_16x16x32_bf16 v[56:59], v[200:203], v[156:159], v[56:59]
	v_mfma_f32_16x16x32_bf16 v[60:63], v[208:211], v[156:159], v[60:63]
	v_mfma_f32_16x16x32_bf16 v[64:67], v[200:203], v[164:167], v[64:67]
	v_mfma_f32_16x16x32_bf16 v[68:71], v[208:211], v[164:167], v[68:71]
	v_mfma_f32_16x16x32_bf16 v[72:75], v[200:203], v[172:175], v[72:75]
	v_mfma_f32_16x16x32_bf16 v[76:79], v[208:211], v[172:175], v[76:79]
	v_mfma_f32_16x16x32_bf16 v[80:83], v[200:203], v[180:183], v[80:83]
	v_mfma_f32_16x16x32_bf16 v[84:87], v[208:211], v[180:183], v[84:87]
	s_setprio 0
	s_barrier
	s_nop 0
	ds_read_b128 v[152:155], v186 offset:49168
	ds_read_b128 v[156:159], v187 offset:49168
	ds_read_b128 v[160:163], v186 offset:51216
	ds_read_b128 v[164:167], v187 offset:51216
	ds_read_b128 v[168:171], v186 offset:53264
	ds_read_b128 v[172:175], v187 offset:53264
	ds_read_b128 v[176:179], v186 offset:55312
	ds_read_b128 v[180:183], v187 offset:55312
	s_add_i32 m0, s39, 0x18000
	s_nop 0
	global_load_lds_dwordx4 v184, s[70:71]
	s_add_i32 m0, s39, 0x18400
	s_nop 0
	global_load_lds_dwordx4 v185, s[70:71]
	s_add_u32 s70, s70, 0x80
	s_addc_u32 s71, s71, 0
	s_add_i32 m0, s39, 0x8000
	s_nop 0
	global_load_lds_dwordx4 v184, s[66:67]
	s_add_i32 m0, s39, 0x8400
	s_nop 0
	global_load_lds_dwordx4 v185, s[66:67]
	s_add_u32 s66, s66, 0x80
	s_addc_u32 s67, s67, 0
	s_add_i32 m0, s39, 0x1c000
	s_nop 0
	global_load_lds_dwordx4 v184, s[72:73]
	s_add_i32 m0, s39, 0x1c400
	s_nop 0
	global_load_lds_dwordx4 v185, s[72:73]
	s_add_u32 s72, s72, 0x80
	s_addc_u32 s73, s73, 0
	s_waitcnt lgkmcnt(0)
	s_waitcnt vmcnt(8)
	s_barrier
	s_setprio 1
	v_mfma_f32_16x16x32_bf16 v[88:91], v[0:3], v[152:155], v[88:91]
	v_mfma_f32_16x16x32_bf16 v[92:95], v[8:11], v[152:155], v[92:95]
	v_mfma_f32_16x16x32_bf16 v[96:99], v[0:3], v[160:163], v[96:99]
	v_mfma_f32_16x16x32_bf16 v[100:103], v[8:11], v[160:163], v[100:103]
	v_mfma_f32_16x16x32_bf16 v[104:107], v[0:3], v[168:171], v[104:107]
	v_mfma_f32_16x16x32_bf16 v[108:111], v[8:11], v[168:171], v[108:111]
	v_mfma_f32_16x16x32_bf16 v[112:115], v[0:3], v[176:179], v[112:115]
	v_mfma_f32_16x16x32_bf16 v[116:119], v[8:11], v[176:179], v[116:119]
	v_mfma_f32_16x16x32_bf16 v[88:91], v[4:7], v[156:159], v[88:91]
	v_mfma_f32_16x16x32_bf16 v[92:95], v[12:15], v[156:159], v[92:95]
	v_mfma_f32_16x16x32_bf16 v[96:99], v[4:7], v[164:167], v[96:99]
	v_mfma_f32_16x16x32_bf16 v[100:103], v[12:15], v[164:167], v[100:103]
	v_mfma_f32_16x16x32_bf16 v[104:107], v[4:7], v[172:175], v[104:107]
	v_mfma_f32_16x16x32_bf16 v[108:111], v[12:15], v[172:175], v[108:111]
	v_mfma_f32_16x16x32_bf16 v[112:115], v[4:7], v[180:183], v[112:115]
	v_mfma_f32_16x16x32_bf16 v[116:119], v[12:15], v[180:183], v[116:119]
	v_mfma_f32_16x16x32_bf16 v[120:123], v[196:199], v[152:155], v[120:123]
	v_mfma_f32_16x16x32_bf16 v[124:127], v[204:207], v[152:155], v[124:127]
	v_mfma_f32_16x16x32_bf16 v[128:131], v[196:199], v[160:163], v[128:131]
	v_mfma_f32_16x16x32_bf16 v[132:135], v[204:207], v[160:163], v[132:135]
	v_mfma_f32_16x16x32_bf16 v[136:139], v[196:199], v[168:171], v[136:139]
	v_mfma_f32_16x16x32_bf16 v[140:143], v[204:207], v[168:171], v[140:143]
	v_mfma_f32_16x16x32_bf16 v[144:147], v[196:199], v[176:179], v[144:147]
	v_mfma_f32_16x16x32_bf16 v[148:151], v[204:207], v[176:179], v[148:151]
	v_mfma_f32_16x16x32_bf16 v[120:123], v[200:203], v[156:159], v[120:123]
	v_mfma_f32_16x16x32_bf16 v[124:127], v[208:211], v[156:159], v[124:127]
	v_mfma_f32_16x16x32_bf16 v[128:131], v[200:203], v[164:167], v[128:131]
	v_mfma_f32_16x16x32_bf16 v[132:135], v[208:211], v[164:167], v[132:135]
	v_mfma_f32_16x16x32_bf16 v[136:139], v[200:203], v[172:175], v[136:139]
	v_mfma_f32_16x16x32_bf16 v[140:143], v[208:211], v[172:175], v[140:143]
	v_mfma_f32_16x16x32_bf16 v[144:147], v[200:203], v[180:183], v[144:147]
	v_mfma_f32_16x16x32_bf16 v[148:151], v[208:211], v[180:183], v[148:151]
	s_setprio 0
	s_barrier
	s_nop 0
	s_sub_u32 s0, s0, 1
	s_cmp_lg_u32 s0, 0
	s_cbranch_scc1 .Lgyd_kloop
